# attention work queue: next item ticket fetched at the start of the current item's epilogue (overlaps the atomic round trip); single bpermute index register
# speedup vs baseline: 1.0043x; 1.0030x over previous
; __device__ __forceinline__ void attn_phase(const Params& p, unsigned char* lds) {
;     ...
;   for (;;) {
;     __syncthreads();
.LBB0_1726:
	s_or_b64 exec, exec, s[0:1]
	s_waitcnt lgkmcnt(0)
	s_barrier
	s_mov_b32 s98, 0
	s_branch .LBB0_1730

; DEVI int otid() { int t = threadIdx.x; asm volatile("" : "+v"(t)); return t; }
; __device__ __forceinline__ void attn_phase(const Params& p, unsigned char* lds) {
;     ...
;     __syncthreads();
;     if (otid() == 0) s_item = (int)atomicAdd(ctr, 1u);
.LBB0_1730:
	v_mov_b32_e32 v0, v128
	s_barrier
	s_nop 0
	v_cmp_eq_u32_e32 vcc, 0, v0
	s_and_saveexec_b64 s[0:1], vcc
	s_cbranch_execz .LBB0_1734
	s_mov_b64 s[4:5], exec
	v_mbcnt_lo_u32_b32 v0, s4, 0
	v_mbcnt_hi_u32_b32 v0, s5, v0
	v_cmp_eq_u32_e32 vcc, 0, v0
	s_and_saveexec_b64 s[2:3], vcc
	s_cbranch_execz .LBB0_1733
	s_cmp_eq_u32 s98, 1
	s_cbranch_scc0 .Lapf_fresh
	s_waitcnt vmcnt(0)
	v_mov_b32_e32 v1, v251
	s_branch .LBB0_1733
.Lapf_fresh:
	s_bcnt1_i32_b64 s4, s[4:5]
	v_mov_b32_e32 v1, s4
	v_readlane_b32 s4, v254, 47
	v_readlane_b32 s5, v254, 48
	s_nop 4
	global_atomic_add v1, v130, v1, s[4:5] sc0

; template <int DK, bool BIAS> ...
;     ...
; #pragma unroll
;   for (int qi = 0; qi < 2; ++qi) {
;     const int qg = q0 + 32 * w + 16 * qi + fr;
; #pragma unroll
;     for (int ks = 0; ks < KS; ++ks) { uint4 u = make_uint4(0, 0, 0, 0); if (qg < qend) u = *(const uint4*)(Qp + (size_t)(rowb + qg) * ldq + 32 * ks + 8 * fq); qf[qi][ks] = mk8u(u); }
;   }
; __device__ __forceinline__ void attn_phase(const Params& p, unsigned char* lds) {
;     ...
;     const int it = s_item;
;     if (it >= 17 * 128) break;
;     const int k = 16 - it / 128, rem = it & 127, type = rem & 1, hh = (rem >> 1) & 7, b = rem >> 4;
;     const int q0 = k ? 16 + 256 * (k - 1) : 0, qend = k ? q0 + 256 : 16, nkv = k ? 4 * k + 1 : 1;
;     if (type == 0)
;       attn_item<96, false>(lds, QR + hh * 96, 768, KV + hh * 128, 1024, KR, 32, KV + hh * 128 + 64, 1024, nullptr, Y + hh * 64, b, q0, qend, nkv, 0.10206207261596575f);
;     else
;       attn_item<64, true>(lds, Zo + 672 + hh * 64, LDZO, Zo + 1184 + hh * 64, LDZO, nullptr, 0, Zo + 1696 + hh * 64, LDZO, FC + (size_t)(b * 8 + hh) * T, Y + 512 + hh * 64, b, q0, qend, nkv, 0.125f);
.LBB0_1734:
	s_mov_b32 s98, 0
	s_or_b64 exec, exec, s[0:1]
	s_waitcnt lgkmcnt(0)
	s_barrier
	ds_read_b32 v0, v182
	s_movk_i32 s0, 0x87f
	s_waitcnt lgkmcnt(0)
	v_cmp_lt_i32_e32 vcc, s0, v0
	v_readfirstlane_b32 s2, v0
	s_mov_b64 s[0:1], -1
	s_cbranch_vccnz .LBB0_1729
	s_ashr_i32 s0, s2, 31
	s_lshr_b32 s0, s0, 25
	s_add_i32 s0, s2, s0
	s_ashr_i32 s0, s0, 7
	s_sub_i32 s1, 16, s0
	s_bfe_u32 s20, s2, 0x30001
	s_bfe_u32 s42, s2, 0x30004
	s_cmp_lg_u32 s1, 0
	s_cselect_b64 s[10:11], -1, 0
	s_lshl_b32 s0, s0, 8
	s_sub_i32 s3, 0xf10, s0
	s_sub_i32 s0, 0x1010, s0
	s_cmp_eq_u32 s1, 0
	s_cselect_b32 s35, 0, s3
	s_cselect_b32 s43, 16, s0
	s_lshl_b32 s21, s1, 2
	s_bitcmp1_b32 s2, 0
	s_cselect_b64 s[0:1], -1, 0
	s_and_b64 vcc, exec, s[0:1]
	s_mul_i32 s58, s42, 0x1010
	s_cbranch_vccz .LBB0_1756
	v_mov_b32_e32 v102, v128
	s_lshl_b32 s0, s20, 7
	v_readlane_b32 s1, v254, 49
	s_add_u32 s0, s1, s0
	s_waitcnt vmcnt(0)
	v_ashrrev_i32_e32 v24, 6, v102
	v_readlane_b32 s1, v254, 50
	v_and_b32_e32 v37, 15, v102
	v_bfe_u32 v36, v102, 4, 2
	v_lshl_add_u32 v127, v24, 5, s35
	s_addc_u32 s1, s1, 0
	v_or_b32_e32 v158, v127, v37
	v_lshlrev_b32_e32 v104, 4, v36
	v_mov_b32_e32 v105, v130
	v_lshl_add_u64 v[8:9], s[0:1], 0, v[104:105]
	v_add_u32_e32 v100, s58, v158
	v_cmp_gt_i32_e64 s[4:5], s43, v158
	v_mad_i64_i32 v[10:11], s[0:1], v100, s53, v[8:9]
	v_mov_b32_e32 v0, 0
	v_mov_b32_e32 v4, 0
	v_mov_b32_e32 v5, 0
	v_mov_b32_e32 v6, 0
	v_mov_b32_e32 v7, 0
	s_and_saveexec_b64 s[0:1], s[4:5]
	s_cbranch_execz .LBB0_1738
	global_load_dwordx4 v[4:7], v[10:11], off

; DEVI unsigned pk_bf16(float lo, float hi) { unsigned r; asm("v_cvt_pk_bf16_f32 %0, %1, %2" : "=v"(r) : "v"(lo), "v"(hi)); return r; }
; DEVI bf16x8 mk8(uint2 a, uint2 b) { union { uint4 u; bf16x8 v; } c; c.u = make_uint4(a.x, a.y, b.x, b.y); return c.v; }
; template <int DK, bool BIAS> ...
;     ...
;       for (int qi = 0; qi < 2; ++qi) {
;         float mx = -3e38f;
;         if (BIAS) {
; #pragma unroll
;           for (int kt = 0; kt < 4; ++kt) { const f32x4 nf = *(const f32x4*)(fkm + buf * 64 + 16 * kt + 4 * fq);
; #pragma unroll
;             for (int r = 0; r < 4; ++r) { const float t = fmaf(S[kt][qi][r], sc2, nf[r]); S[kt][qi][r] = t; mx = fmaxf(mx, t); } }
;         } else {
; #pragma unroll
;           for (int kt = 0; kt < 4; ++kt)
; #pragma unroll
;             for (int r = 0; r < 4; ++r) mx = fmaxf(mx, S[kt][qi][r]);
;           mx *= sc2;
;         }
;         mx = fmaxf(mx, __shfl_xor(mx, 16)); mx = fmaxf(mx, __shfl_xor(mx, 32));
;         const float mold = mrun[qi], mnew = fmaxf(mold, mx);
;         mrun[qi] = mnew;
;         float ps = 0.f;
; #pragma unroll
;         for (int kt = 0; kt < 4; ++kt)
; #pragma unroll
;           for (int r = 0; r < 4; ++r) { const float pv = BIAS ? __builtin_amdgcn_exp2f(S[kt][qi][r] - mnew) : __builtin_amdgcn_exp2f(fmaf(S[kt][qi][r], sc2, -mnew)); S[kt][qi][r] = pv; ps += pv; }
;         {
;           const float alpha = __builtin_amdgcn_exp2f(mold - mnew);
;           lrun[qi] *= alpha;
; #pragma unroll
;           for (int et = 0; et < 4; ++et) O[et][qi] *= alpha;
;         }
;         lrun[qi] += ps;
; #pragma unroll
;         for (int k2 = 0; k2 < 2; ++k2) { uint2 lo, hi; lo.x = pk_bf16(S[2 * k2][qi][0], S[2 * k2][qi][1]); lo.y = pk_bf16(S[2 * k2][qi][2], S[2 * k2][qi][3]);
;           hi.x = pk_bf16(S[2 * k2 + 1][qi][0], S[2 * k2 + 1][qi][1]); hi.y = pk_bf16(S[2 * k2 + 1][qi][2], S[2 * k2 + 1][qi][3]); pf[qi][k2] = mk8(lo, hi); }
;       }
.LBB0_1776:
	s_or_b64 exec, exec, s[18:19]
	ds_read_b128 v[174:177], v168 offset:36864
	ds_read_b128 v[194:197], v168 offset:36928
	ds_read_b128 v[242:245], v168 offset:36992
	ds_read_b128 v[246:249], v168 offset:37056
	s_mov_b32 s100, 0x3e38aa3b
	s_mov_b32 s101, 0x3e38aa3b
	v_lshlrev_b32_e32 v250, 2, v186
	s_waitcnt lgkmcnt(3)
	v_pk_fma_f32 v[210:211], v[80:81], s[100:101], v[174:175]
	v_pk_fma_f32 v[212:213], v[82:83], s[100:101], v[176:177]
	v_pk_fma_f32 v[226:227], v[64:65], s[100:101], v[174:175]
	v_pk_fma_f32 v[228:229], v[66:67], s[100:101], v[176:177]
	s_waitcnt lgkmcnt(2)
	v_pk_fma_f32 v[214:215], v[86:87], s[100:101], v[194:195]
	v_pk_fma_f32 v[216:217], v[88:89], s[100:101], v[196:197]
	v_pk_fma_f32 v[230:231], v[68:69], s[100:101], v[194:195]
	v_pk_fma_f32 v[232:233], v[70:71], s[100:101], v[196:197]
	s_waitcnt lgkmcnt(1)
	v_pk_fma_f32 v[218:219], v[90:91], s[100:101], v[242:243]
	v_pk_fma_f32 v[220:221], v[92:93], s[100:101], v[244:245]
	v_pk_fma_f32 v[234:235], v[72:73], s[100:101], v[242:243]
	v_pk_fma_f32 v[236:237], v[74:75], s[100:101], v[244:245]
	s_waitcnt lgkmcnt(0)
	v_pk_fma_f32 v[222:223], v[94:95], s[100:101], v[246:247]
	v_pk_fma_f32 v[224:225], v[96:97], s[100:101], v[248:249]
	v_pk_fma_f32 v[238:239], v[76:77], s[100:101], v[246:247]
	v_pk_fma_f32 v[240:241], v[78:79], s[100:101], v[248:249]
	v_max3_f32 v84, v210, s31, v211
	v_max3_f32 v85, v226, s31, v227
	v_max3_f32 v84, v84, v212, v213
	v_max3_f32 v85, v85, v228, v229
	v_max3_f32 v84, v84, v214, v215
	v_max3_f32 v85, v85, v230, v231
	v_max3_f32 v84, v84, v216, v217
	v_max3_f32 v85, v85, v232, v233
	v_max3_f32 v84, v84, v218, v219
	v_max3_f32 v85, v85, v234, v235
	v_max3_f32 v84, v84, v220, v221
	v_max3_f32 v85, v85, v236, v237
	v_max3_f32 v84, v84, v222, v223
	v_max3_f32 v85, v85, v238, v239
	v_max3_f32 v84, v84, v224, v225
	v_max3_f32 v85, v85, v240, v241
	ds_bpermute_b32 v86, v250, v84
	ds_bpermute_b32 v87, v250, v85
	s_waitcnt lgkmcnt(0)
	v_max_f32_e32 v84, v84, v86
	v_max_f32_e32 v85, v85, v87
	v_lshlrev_b32_e32 v250, 2, v185
	ds_bpermute_b32 v86, v250, v84
	ds_bpermute_b32 v87, v250, v85
	s_waitcnt lgkmcnt(0)
	v_max3_f32 v131, v114, v84, v86
	v_max3_f32 v173, v112, v85, v87
	v_sub_f32_e32 v84, v114, v131
	v_sub_f32_e32 v85, v112, v173
	v_exp_f32_e32 v126, v84
	v_exp_f32_e32 v82, v85
	v_sub_f32_e32 v86, 0, v131
	v_sub_f32_e32 v80, 0, v173
	v_pk_add_f32 v[210:211], v[210:211], v[86:87] op_sel_hi:[1,0]
	v_pk_add_f32 v[212:213], v[212:213], v[86:87] op_sel_hi:[1,0]
	v_pk_add_f32 v[226:227], v[226:227], v[80:81] op_sel_hi:[1,0]
	v_pk_add_f32 v[228:229], v[228:229], v[80:81] op_sel_hi:[1,0]
	v_pk_add_f32 v[214:215], v[214:215], v[86:87] op_sel_hi:[1,0]
	v_pk_add_f32 v[216:217], v[216:217], v[86:87] op_sel_hi:[1,0]
	v_pk_add_f32 v[230:231], v[230:231], v[80:81] op_sel_hi:[1,0]
	v_pk_add_f32 v[232:233], v[232:233], v[80:81] op_sel_hi:[1,0]
	v_pk_add_f32 v[218:219], v[218:219], v[86:87] op_sel_hi:[1,0]
	v_pk_add_f32 v[220:221], v[220:221], v[86:87] op_sel_hi:[1,0]
	v_pk_add_f32 v[234:235], v[234:235], v[80:81] op_sel_hi:[1,0]
	v_pk_add_f32 v[236:237], v[236:237], v[80:81] op_sel_hi:[1,0]
	v_pk_add_f32 v[222:223], v[222:223], v[86:87] op_sel_hi:[1,0]
	v_pk_add_f32 v[224:225], v[224:225], v[86:87] op_sel_hi:[1,0]
	v_pk_add_f32 v[238:239], v[238:239], v[80:81] op_sel_hi:[1,0]
	v_pk_add_f32 v[240:241], v[240:241], v[80:81] op_sel_hi:[1,0]
	v_exp_f32_e32 v155, v210
	v_exp_f32_e32 v154, v226
	v_exp_f32_e32 v157, v211
	v_exp_f32_e32 v156, v227
	v_exp_f32_e32 v151, v212
	v_exp_f32_e32 v150, v228
	v_exp_f32_e32 v153, v213
	v_exp_f32_e32 v152, v229
	v_exp_f32_e32 v117, v214
	v_exp_f32_e32 v116, v230
	v_exp_f32_e32 v119, v215
	v_exp_f32_e32 v118, v231
	v_exp_f32_e32 v123, v216
	v_exp_f32_e32 v122, v232
	v_exp_f32_e32 v121, v217
	v_exp_f32_e32 v120, v233
	v_exp_f32_e32 v125, v218
	v_exp_f32_e32 v124, v234
	v_exp_f32_e32 v89, v219
	v_exp_f32_e32 v88, v235
	v_exp_f32_e32 v95, v220
	v_exp_f32_e32 v94, v236
	v_exp_f32_e32 v115, v221
	v_exp_f32_e32 v114, v237
	v_exp_f32_e32 v93, v222
	v_exp_f32_e32 v92, v238
	v_exp_f32_e32 v113, v223
	v_exp_f32_e32 v112, v239
	v_exp_f32_e32 v91, v224
	v_exp_f32_e32 v90, v240
	v_exp_f32_e32 v97, v225
	v_exp_f32_e32 v96, v241
	v_pk_mul_f32 v[202:203], v[52:53], v[126:127] op_sel_hi:[1,0]
	v_pk_mul_f32 v[52:53], v[56:57], v[126:127] op_sel_hi:[1,0]
	v_pk_mul_f32 v[198:199], v[48:49], v[126:127] op_sel_hi:[1,0]
	v_pk_mul_f32 v[48:49], v[60:61], v[126:127] op_sel_hi:[1,0]
	v_add_u32_e32 v174, 0x4800, v170
	v_add_u32_e32 v175, 0x5000, v170
	v_pk_mul_f32 v[200:201], v[50:51], v[126:127] op_sel_hi:[1,0]
	v_add_u32_e32 v176, 0x5800, v170
	v_pk_mul_f32 v[204:205], v[54:55], v[126:127] op_sel_hi:[1,0]
	v_pk_add_f32 v[64:65], v[154:155], 0 op_sel_hi:[1,0]
	v_pk_add_f32 v[80:81], v[156:157], v[64:65]
	ds_read2_b64 v[64:67], v174 offset1:4
	ds_read2_b64 v[72:75], v175 offset0:32 offset1:36
	v_pk_mul_f32 v[46:47], v[46:47], v[82:83] op_sel_hi:[1,0]
	v_pk_mul_f32 v[44:45], v[44:45], v[82:83] op_sel_hi:[1,0]
	v_pk_mul_f32 v[54:55], v[58:59], v[126:127] op_sel_hi:[1,0]
	v_cvt_pk_bf16_f32 v56, v155, v157
	v_cvt_pk_bf16_f32 v57, v151, v153
	v_cvt_pk_bf16_f32 v58, v117, v119
	v_cvt_pk_bf16_f32 v59, v123, v121
	v_cvt_pk_bf16_f32 v68, v154, v156
	s_waitcnt lgkmcnt(1)
; DEVI unsigned pk_bf16(float lo, float hi) { unsigned r; asm("v_cvt_pk_bf16_f32 %0, %1, %2" : "=v"(r) : "v"(lo), "v"(hi)); return r; }
; DEVI bf16x8 mk8(uint2 a, uint2 b) { union { uint4 u; bf16x8 v; } c; c.u = make_uint4(a.x, a.y, b.x, b.y); return c.v; }
; #define MFMA(a, b, c) __builtin_amdgcn_mfma_f32_16x16x32_bf16((a), (b), (c), 0, 0, 0)
; template <int DK, bool BIAS> ...
;     ...
;         float ps = 0.f;
; #pragma unroll
;         for (int kt = 0; kt < 4; ++kt)
; #pragma unroll
;           for (int r = 0; r < 4; ++r) { const float pv = BIAS ? __builtin_amdgcn_exp2f(S[kt][qi][r] - mnew) : __builtin_amdgcn_exp2f(fmaf(S[kt][qi][r], sc2, -mnew)); S[kt][qi][r] = pv; ps += pv; }
;         {
;           const float alpha = __builtin_amdgcn_exp2f(mold - mnew);
;           lrun[qi] *= alpha;
; #pragma unroll
;           for (int et = 0; et < 4; ++et) O[et][qi] *= alpha;
;         }
;         lrun[qi] += ps;
; #pragma unroll
;         for (int k2 = 0; k2 < 2; ++k2) { uint2 lo, hi; lo.x = pk_bf16(S[2 * k2][qi][0], S[2 * k2][qi][1]); lo.y = pk_bf16(S[2 * k2][qi][2], S[2 * k2][qi][3]);
;           hi.x = pk_bf16(S[2 * k2 + 1][qi][0], S[2 * k2 + 1][qi][1]); hi.y = pk_bf16(S[2 * k2 + 1][qi][2], S[2 * k2 + 1][qi][3]); pf[qi][k2] = mk8(lo, hi); }
;       }
; #pragma unroll
;       for (int k2 = 0; k2 < 2; ++k2)
; #pragma unroll
;         for (int et = 0; et < 4; ++et) {
;           const uint2 v0 = *(const uint2*)(Vtm + (buf * 64 + 16 * et + fr) * 72 + 32 * k2 + 4 * fq), v1 = *(const uint2*)(Vtm + (buf * 64 + 16 * et + fr) * 72 + 32 * k2 + 16 + 4 * fq);
;           const bf16x8 va = mk8(v0, v1);
; #pragma unroll
;           for (int qi = 0; qi < 2; ++qi) O[et][qi] = MFMA(va, pf[qi][k2], O[et][qi]);
;         }
	v_mfma_f32_16x16x32_bf16 v[76:79], v[64:67], v[56:59], v[198:201]
	v_cvt_pk_bf16_f32 v69, v150, v152
	v_cvt_pk_bf16_f32 v70, v116, v118
	v_cvt_pk_bf16_f32 v71, v122, v120
	v_pk_mul_f32 v[42:43], v[42:43], v[82:83] op_sel_hi:[1,0]
	s_nop 0
	v_mfma_f32_16x16x32_bf16 v[44:47], v[64:67], v[68:71], v[44:47]
	ds_read2_b64 v[64:67], v176 offset0:64 offset1:68
	v_pk_mul_f32 v[40:41], v[40:41], v[82:83] op_sel_hi:[1,0]
	v_add_u32_e32 v177, 0x6000, v170
	s_waitcnt lgkmcnt(1)
	v_mfma_f32_16x16x32_bf16 v[84:87], v[72:75], v[56:59], v[202:205]
	v_pk_mul_f32 v[50:51], v[62:63], v[126:127] op_sel_hi:[1,0]
	v_mfma_f32_16x16x32_bf16 v[40:43], v[72:75], v[68:71], v[40:43]
	ds_read2_b64 v[72:75], v177 offset0:96 offset1:100
	v_pk_mul_f32 v[38:39], v[38:39], v[82:83] op_sel_hi:[1,0]
	v_pk_mul_f32 v[36:37], v[36:37], v[82:83] op_sel_hi:[1,0]
	s_waitcnt lgkmcnt(1)
	v_mfma_f32_16x16x32_bf16 v[154:157], v[64:67], v[56:59], v[52:55]
	v_pk_mul_f32 v[34:35], v[34:35], v[82:83] op_sel_hi:[1,0]
	v_pk_mul_f32 v[32:33], v[32:33], v[82:83] op_sel_hi:[1,0]
	v_cvt_pk_bf16_f32 v60, v125, v89
	v_mfma_f32_16x16x32_bf16 v[36:39], v[64:67], v[68:71], v[36:39]
	ds_read2_b64 v[52:55], v174 offset0:8 offset1:12
	s_waitcnt lgkmcnt(1)
	v_mfma_f32_16x16x32_bf16 v[64:67], v[72:75], v[56:59], v[48:51]
	ds_read2_b64 v[56:59], v175 offset0:40 offset1:44
	v_cvt_pk_bf16_f32 v61, v95, v115
	v_cvt_pk_bf16_f32 v62, v93, v113
	v_cvt_pk_bf16_f32 v63, v91, v97
	s_nop 0
	v_mfma_f32_16x16x32_bf16 v[32:35], v[72:75], v[68:71], v[32:35]
	v_cvt_pk_bf16_f32 v68, v124, v88
	v_cvt_pk_bf16_f32 v69, v94, v114
	s_waitcnt lgkmcnt(1)
	v_mfma_f32_16x16x32_bf16 v[48:51], v[52:55], v[60:63], v[76:79]
	v_cvt_pk_bf16_f32 v70, v92, v112
	v_cvt_pk_bf16_f32 v71, v90, v96
	ds_read2_b64 v[72:75], v176 offset0:72 offset1:76
	s_nop 0
	v_mfma_f32_16x16x32_bf16 v[44:47], v[52:55], v[68:71], v[44:47]
	v_pk_add_f32 v[52:53], v[150:151], v[80:81]
	v_mov_b32_e32 v83, v126
	v_pk_add_f32 v[76:77], v[152:153], v[52:53]
	s_waitcnt lgkmcnt(1)
	v_mfma_f32_16x16x32_bf16 v[52:55], v[56:59], v[60:63], v[84:87]
	v_pk_add_f32 v[76:77], v[116:117], v[76:77]
	v_pk_add_f32 v[76:77], v[118:119], v[76:77]
	v_mfma_f32_16x16x32_bf16 v[40:43], v[56:59], v[68:71], v[40:43]
	v_pk_add_f32 v[76:77], v[122:123], v[76:77]
	v_pk_add_f32 v[56:57], v[120:121], v[76:77]
	ds_read2_b64 v[76:79], v177 offset0:104 offset1:108
	v_pk_add_f32 v[80:81], v[124:125], v[56:57]
	s_waitcnt lgkmcnt(1)
	v_mfma_f32_16x16x32_bf16 v[56:59], v[72:75], v[60:63], v[154:157]
	v_pk_add_f32 v[80:81], v[88:89], v[80:81]
	v_pk_add_f32 v[80:81], v[94:95], v[80:81]
	v_mfma_f32_16x16x32_bf16 v[36:39], v[72:75], v[68:71], v[36:39]
	v_pk_add_f32 v[80:81], v[114:115], v[80:81]
	v_mov_b32_e32 v114, v131
	v_pk_add_f32 v[72:73], v[92:93], v[80:81]
	s_waitcnt lgkmcnt(0)
	v_mfma_f32_16x16x32_bf16 v[60:63], v[76:79], v[60:63], v[64:67]
	v_pk_add_f32 v[72:73], v[112:113], v[72:73]
	v_mov_b32_e32 v112, v173
	v_mfma_f32_16x16x32_bf16 v[32:35], v[76:79], v[68:71], v[32:35]
	v_pk_add_f32 v[64:65], v[90:91], v[72:73]
	v_pk_add_f32 v[64:65], v[96:97], v[64:65]
	s_nop 0
	v_pk_fma_f32 v[106:107], v[106:107], v[82:83], v[64:65]

; DEVI unsigned pk_bf16(float lo, float hi) { unsigned r; asm("v_cvt_pk_bf16_f32 %0, %1, %2" : "=v"(r) : "v"(lo), "v"(hi)); return r; }
; DEVI bf16x8 mk8(uint2 a, uint2 b) { union { uint4 u; bf16x8 v; } c; c.u = make_uint4(a.x, a.y, b.x, b.y); return c.v; }
; template <int DK, bool BIAS> ...
;     ...
;       for (int qi = 0; qi < 2; ++qi) {
;         float mx = -3e38f;
;         if (BIAS) {
; #pragma unroll
;           for (int kt = 0; kt < 4; ++kt) { const f32x4 nf = *(const f32x4*)(fkm + buf * 64 + 16 * kt + 4 * fq);
; #pragma unroll
;             for (int r = 0; r < 4; ++r) { const float t = fmaf(S[kt][qi][r], sc2, nf[r]); S[kt][qi][r] = t; mx = fmaxf(mx, t); } }
;         } else {
; #pragma unroll
;           for (int kt = 0; kt < 4; ++kt)
; #pragma unroll
;             for (int r = 0; r < 4; ++r) mx = fmaxf(mx, S[kt][qi][r]);
;           mx *= sc2;
;         }
;         mx = fmaxf(mx, __shfl_xor(mx, 16)); mx = fmaxf(mx, __shfl_xor(mx, 32));
;         const float mold = mrun[qi], mnew = fmaxf(mold, mx);
;         mrun[qi] = mnew;
;         float ps = 0.f;
; #pragma unroll
;         for (int kt = 0; kt < 4; ++kt)
; #pragma unroll
;           for (int r = 0; r < 4; ++r) { const float pv = BIAS ? __builtin_amdgcn_exp2f(S[kt][qi][r] - mnew) : __builtin_amdgcn_exp2f(fmaf(S[kt][qi][r], sc2, -mnew)); S[kt][qi][r] = pv; ps += pv; }
;         {
;           const float alpha = __builtin_amdgcn_exp2f(mold - mnew);
;           lrun[qi] *= alpha;
; #pragma unroll
;           for (int et = 0; et < 4; ++et) O[et][qi] *= alpha;
;         }
;         lrun[qi] += ps;
; #pragma unroll
;         for (int k2 = 0; k2 < 2; ++k2) { uint2 lo, hi; lo.x = pk_bf16(S[2 * k2][qi][0], S[2 * k2][qi][1]); lo.y = pk_bf16(S[2 * k2][qi][2], S[2 * k2][qi][3]);
;           hi.x = pk_bf16(S[2 * k2 + 1][qi][0], S[2 * k2 + 1][qi][1]); hi.y = pk_bf16(S[2 * k2 + 1][qi][2], S[2 * k2 + 1][qi][3]); pf[qi][k2] = mk8(lo, hi); }
;       }
.LBB0_1797:
	s_or_b64 exec, exec, s[18:19]
	ds_read_b128 v[174:177], v104 offset:37120
	ds_read_b128 v[194:197], v104 offset:37184
	ds_read_b128 v[242:245], v104 offset:37248
	ds_read_b128 v[246:249], v104 offset:37312
	s_mov_b32 s100, 0x3e38aa3b
	s_mov_b32 s101, 0x3e38aa3b
	v_lshlrev_b32_e32 v250, 2, v186
	s_waitcnt lgkmcnt(3)
	v_pk_fma_f32 v[210:211], v[80:81], s[100:101], v[174:175]
	v_pk_fma_f32 v[212:213], v[82:83], s[100:101], v[176:177]
	v_pk_fma_f32 v[226:227], v[64:65], s[100:101], v[174:175]
	v_pk_fma_f32 v[228:229], v[66:67], s[100:101], v[176:177]
	s_waitcnt lgkmcnt(2)
	v_pk_fma_f32 v[214:215], v[86:87], s[100:101], v[194:195]
	v_pk_fma_f32 v[216:217], v[88:89], s[100:101], v[196:197]
	v_pk_fma_f32 v[230:231], v[68:69], s[100:101], v[194:195]
	v_pk_fma_f32 v[232:233], v[70:71], s[100:101], v[196:197]
	s_waitcnt lgkmcnt(1)
	v_pk_fma_f32 v[218:219], v[90:91], s[100:101], v[242:243]
	v_pk_fma_f32 v[220:221], v[92:93], s[100:101], v[244:245]
	v_pk_fma_f32 v[234:235], v[72:73], s[100:101], v[242:243]
	v_pk_fma_f32 v[236:237], v[74:75], s[100:101], v[244:245]
	s_waitcnt lgkmcnt(0)
	v_pk_fma_f32 v[222:223], v[94:95], s[100:101], v[246:247]
	v_pk_fma_f32 v[224:225], v[96:97], s[100:101], v[248:249]
	v_pk_fma_f32 v[238:239], v[76:77], s[100:101], v[246:247]
	v_pk_fma_f32 v[240:241], v[78:79], s[100:101], v[248:249]
	v_max3_f32 v84, v210, s31, v211
	v_max3_f32 v85, v226, s31, v227
	v_max3_f32 v84, v84, v212, v213
	v_max3_f32 v85, v85, v228, v229
	v_max3_f32 v84, v84, v214, v215
	v_max3_f32 v85, v85, v230, v231
	v_max3_f32 v84, v84, v216, v217
	v_max3_f32 v85, v85, v232, v233
	v_max3_f32 v84, v84, v218, v219
	v_max3_f32 v85, v85, v234, v235
	v_max3_f32 v84, v84, v220, v221
	v_max3_f32 v85, v85, v236, v237
	v_max3_f32 v84, v84, v222, v223
	v_max3_f32 v85, v85, v238, v239
	v_max3_f32 v84, v84, v224, v225
	v_max3_f32 v85, v85, v240, v241
	ds_bpermute_b32 v86, v250, v84
	ds_bpermute_b32 v87, v250, v85
	s_waitcnt lgkmcnt(0)
	v_max_f32_e32 v84, v84, v86
	v_max_f32_e32 v85, v85, v87
	v_lshlrev_b32_e32 v250, 2, v185
	ds_bpermute_b32 v86, v250, v84
	ds_bpermute_b32 v87, v250, v85
	s_waitcnt lgkmcnt(0)
	v_max3_f32 v131, v114, v84, v86
	v_max3_f32 v173, v112, v85, v87
	v_sub_f32_e32 v84, v114, v131
	v_sub_f32_e32 v85, v112, v173
	v_exp_f32_e32 v126, v84
	v_exp_f32_e32 v82, v85
	v_sub_f32_e32 v86, 0, v131
	v_sub_f32_e32 v80, 0, v173
	v_pk_add_f32 v[210:211], v[210:211], v[86:87] op_sel_hi:[1,0]
	v_pk_add_f32 v[212:213], v[212:213], v[86:87] op_sel_hi:[1,0]
	v_pk_add_f32 v[226:227], v[226:227], v[80:81] op_sel_hi:[1,0]
	v_pk_add_f32 v[228:229], v[228:229], v[80:81] op_sel_hi:[1,0]
	v_pk_add_f32 v[214:215], v[214:215], v[86:87] op_sel_hi:[1,0]
	v_pk_add_f32 v[216:217], v[216:217], v[86:87] op_sel_hi:[1,0]
	v_pk_add_f32 v[230:231], v[230:231], v[80:81] op_sel_hi:[1,0]
	v_pk_add_f32 v[232:233], v[232:233], v[80:81] op_sel_hi:[1,0]
	v_pk_add_f32 v[218:219], v[218:219], v[86:87] op_sel_hi:[1,0]
	v_pk_add_f32 v[220:221], v[220:221], v[86:87] op_sel_hi:[1,0]
	v_pk_add_f32 v[234:235], v[234:235], v[80:81] op_sel_hi:[1,0]
	v_pk_add_f32 v[236:237], v[236:237], v[80:81] op_sel_hi:[1,0]
	v_pk_add_f32 v[222:223], v[222:223], v[86:87] op_sel_hi:[1,0]
	v_pk_add_f32 v[224:225], v[224:225], v[86:87] op_sel_hi:[1,0]
	v_pk_add_f32 v[238:239], v[238:239], v[80:81] op_sel_hi:[1,0]
	v_pk_add_f32 v[240:241], v[240:241], v[80:81] op_sel_hi:[1,0]
	v_exp_f32_e32 v155, v210
	v_exp_f32_e32 v154, v226
	v_exp_f32_e32 v157, v211
	v_exp_f32_e32 v156, v227
	v_exp_f32_e32 v151, v212
	v_exp_f32_e32 v150, v228
	v_exp_f32_e32 v153, v213
	v_exp_f32_e32 v152, v229
	v_exp_f32_e32 v117, v214
	v_exp_f32_e32 v116, v230
	v_exp_f32_e32 v119, v215
	v_exp_f32_e32 v118, v231
	v_exp_f32_e32 v123, v216
	v_exp_f32_e32 v122, v232
	v_exp_f32_e32 v121, v217
	v_exp_f32_e32 v120, v233
	v_exp_f32_e32 v125, v218
	v_exp_f32_e32 v124, v234
	v_exp_f32_e32 v89, v219
	v_exp_f32_e32 v88, v235
	v_exp_f32_e32 v95, v220
	v_exp_f32_e32 v94, v236
	v_exp_f32_e32 v115, v221
	v_exp_f32_e32 v114, v237
	v_exp_f32_e32 v93, v222
	v_exp_f32_e32 v92, v238
	v_exp_f32_e32 v113, v223
	v_exp_f32_e32 v112, v239
	v_exp_f32_e32 v91, v224
	v_exp_f32_e32 v90, v240
	v_exp_f32_e32 v97, v225
	v_exp_f32_e32 v96, v241
	v_pk_mul_f32 v[202:203], v[52:53], v[126:127] op_sel_hi:[1,0]
	v_pk_mul_f32 v[52:53], v[56:57], v[126:127] op_sel_hi:[1,0]
	v_pk_mul_f32 v[198:199], v[48:49], v[126:127] op_sel_hi:[1,0]
	v_pk_mul_f32 v[48:49], v[60:61], v[126:127] op_sel_hi:[1,0]
	v_add_u32_e32 v174, 0x6800, v170
	v_add_u32_e32 v175, 0x7000, v170
	v_pk_mul_f32 v[200:201], v[50:51], v[126:127] op_sel_hi:[1,0]
	v_add_u32_e32 v176, 0x7800, v170
	v_pk_mul_f32 v[204:205], v[54:55], v[126:127] op_sel_hi:[1,0]
	v_pk_add_f32 v[64:65], v[154:155], 0 op_sel_hi:[1,0]
	v_pk_add_f32 v[80:81], v[156:157], v[64:65]
	ds_read2_b64 v[64:67], v174 offset0:128 offset1:132
	ds_read2_b64 v[72:75], v175 offset0:160 offset1:164
	v_pk_mul_f32 v[46:47], v[46:47], v[82:83] op_sel_hi:[1,0]
	v_pk_mul_f32 v[44:45], v[44:45], v[82:83] op_sel_hi:[1,0]
	v_pk_mul_f32 v[54:55], v[58:59], v[126:127] op_sel_hi:[1,0]
	v_cvt_pk_bf16_f32 v56, v155, v157
	v_cvt_pk_bf16_f32 v57, v151, v153
	v_cvt_pk_bf16_f32 v58, v117, v119
	v_cvt_pk_bf16_f32 v59, v123, v121
	v_cvt_pk_bf16_f32 v68, v154, v156
	s_waitcnt lgkmcnt(1)
; DEVI unsigned pk_bf16(float lo, float hi) { unsigned r; asm("v_cvt_pk_bf16_f32 %0, %1, %2" : "=v"(r) : "v"(lo), "v"(hi)); return r; }
; DEVI bf16x8 mk8(uint2 a, uint2 b) { union { uint4 u; bf16x8 v; } c; c.u = make_uint4(a.x, a.y, b.x, b.y); return c.v; }
; #define MFMA(a, b, c) __builtin_amdgcn_mfma_f32_16x16x32_bf16((a), (b), (c), 0, 0, 0)
; template <int DK, bool BIAS> ...
;     ...
;         float ps = 0.f;
; #pragma unroll
;         for (int kt = 0; kt < 4; ++kt)
; #pragma unroll
;           for (int r = 0; r < 4; ++r) { const float pv = BIAS ? __builtin_amdgcn_exp2f(S[kt][qi][r] - mnew) : __builtin_amdgcn_exp2f(fmaf(S[kt][qi][r], sc2, -mnew)); S[kt][qi][r] = pv; ps += pv; }
;         {
;           const float alpha = __builtin_amdgcn_exp2f(mold - mnew);
;           lrun[qi] *= alpha;
; #pragma unroll
;           for (int et = 0; et < 4; ++et) O[et][qi] *= alpha;
;         }
;         lrun[qi] += ps;
; #pragma unroll
;         for (int k2 = 0; k2 < 2; ++k2) { uint2 lo, hi; lo.x = pk_bf16(S[2 * k2][qi][0], S[2 * k2][qi][1]); lo.y = pk_bf16(S[2 * k2][qi][2], S[2 * k2][qi][3]);
;           hi.x = pk_bf16(S[2 * k2 + 1][qi][0], S[2 * k2 + 1][qi][1]); hi.y = pk_bf16(S[2 * k2 + 1][qi][2], S[2 * k2 + 1][qi][3]); pf[qi][k2] = mk8(lo, hi); }
;       }
; #pragma unroll
;       for (int k2 = 0; k2 < 2; ++k2)
; #pragma unroll
;         for (int et = 0; et < 4; ++et) {
;           const uint2 v0 = *(const uint2*)(Vtm + (buf * 64 + 16 * et + fr) * 72 + 32 * k2 + 4 * fq), v1 = *(const uint2*)(Vtm + (buf * 64 + 16 * et + fr) * 72 + 32 * k2 + 16 + 4 * fq);
;           const bf16x8 va = mk8(v0, v1);
; #pragma unroll
;           for (int qi = 0; qi < 2; ++qi) O[et][qi] = MFMA(va, pf[qi][k2], O[et][qi]);
;         }
	v_mfma_f32_16x16x32_bf16 v[76:79], v[64:67], v[56:59], v[198:201]
	v_cvt_pk_bf16_f32 v69, v150, v152
	v_cvt_pk_bf16_f32 v70, v116, v118
	v_cvt_pk_bf16_f32 v71, v122, v120
	v_pk_mul_f32 v[42:43], v[42:43], v[82:83] op_sel_hi:[1,0]
	s_nop 0
	v_mfma_f32_16x16x32_bf16 v[44:47], v[64:67], v[68:71], v[44:47]
	ds_read2_b64 v[64:67], v176 offset0:192 offset1:196
	v_pk_mul_f32 v[40:41], v[40:41], v[82:83] op_sel_hi:[1,0]
	v_add_u32_e32 v177, 0x8000, v170
	s_waitcnt lgkmcnt(1)
	v_mfma_f32_16x16x32_bf16 v[84:87], v[72:75], v[56:59], v[202:205]
	v_pk_mul_f32 v[50:51], v[62:63], v[126:127] op_sel_hi:[1,0]
	v_mfma_f32_16x16x32_bf16 v[40:43], v[72:75], v[68:71], v[40:43]
	ds_read2_b64 v[72:75], v177 offset0:224 offset1:228
	v_pk_mul_f32 v[38:39], v[38:39], v[82:83] op_sel_hi:[1,0]
	v_pk_mul_f32 v[36:37], v[36:37], v[82:83] op_sel_hi:[1,0]
	s_waitcnt lgkmcnt(1)
	v_mfma_f32_16x16x32_bf16 v[154:157], v[64:67], v[56:59], v[52:55]
	v_pk_mul_f32 v[34:35], v[34:35], v[82:83] op_sel_hi:[1,0]
	v_pk_mul_f32 v[32:33], v[32:33], v[82:83] op_sel_hi:[1,0]
	v_cvt_pk_bf16_f32 v60, v125, v89
	v_mfma_f32_16x16x32_bf16 v[36:39], v[64:67], v[68:71], v[36:39]
	ds_read2_b64 v[52:55], v174 offset0:136 offset1:140
	s_waitcnt lgkmcnt(1)
	v_mfma_f32_16x16x32_bf16 v[64:67], v[72:75], v[56:59], v[48:51]
	ds_read2_b64 v[56:59], v175 offset0:168 offset1:172
	v_cvt_pk_bf16_f32 v61, v95, v115
	v_cvt_pk_bf16_f32 v62, v93, v113
	v_cvt_pk_bf16_f32 v63, v91, v97
	s_nop 0
	v_mfma_f32_16x16x32_bf16 v[32:35], v[72:75], v[68:71], v[32:35]
	v_cvt_pk_bf16_f32 v68, v124, v88
	v_cvt_pk_bf16_f32 v69, v94, v114
	s_waitcnt lgkmcnt(1)
	v_mfma_f32_16x16x32_bf16 v[48:51], v[52:55], v[60:63], v[76:79]
	v_cvt_pk_bf16_f32 v70, v92, v112
	v_cvt_pk_bf16_f32 v71, v90, v96
	ds_read2_b64 v[72:75], v176 offset0:200 offset1:204
	s_nop 0
	v_mfma_f32_16x16x32_bf16 v[44:47], v[52:55], v[68:71], v[44:47]
	v_pk_add_f32 v[52:53], v[150:151], v[80:81]
	v_mov_b32_e32 v83, v126
	v_pk_add_f32 v[76:77], v[152:153], v[52:53]
	s_waitcnt lgkmcnt(1)
	v_mfma_f32_16x16x32_bf16 v[52:55], v[56:59], v[60:63], v[84:87]
	v_pk_add_f32 v[76:77], v[116:117], v[76:77]
	v_pk_add_f32 v[76:77], v[118:119], v[76:77]
	v_mfma_f32_16x16x32_bf16 v[40:43], v[56:59], v[68:71], v[40:43]
	v_pk_add_f32 v[76:77], v[122:123], v[76:77]
	v_pk_add_f32 v[56:57], v[120:121], v[76:77]
	ds_read2_b64 v[76:79], v177 offset0:232 offset1:236
	v_pk_add_f32 v[80:81], v[124:125], v[56:57]
	s_waitcnt lgkmcnt(1)
	v_mfma_f32_16x16x32_bf16 v[56:59], v[72:75], v[60:63], v[154:157]
	v_pk_add_f32 v[80:81], v[88:89], v[80:81]
	v_pk_add_f32 v[80:81], v[94:95], v[80:81]
	v_mfma_f32_16x16x32_bf16 v[36:39], v[72:75], v[68:71], v[36:39]
	v_pk_add_f32 v[80:81], v[114:115], v[80:81]
	v_mov_b32_e32 v114, v131
	v_pk_add_f32 v[72:73], v[92:93], v[80:81]
	s_waitcnt lgkmcnt(0)
	v_mfma_f32_16x16x32_bf16 v[60:63], v[76:79], v[60:63], v[64:67]
	v_pk_add_f32 v[72:73], v[112:113], v[72:73]
	v_mov_b32_e32 v112, v173
	v_mfma_f32_16x16x32_bf16 v[32:35], v[76:79], v[68:71], v[32:35]
	v_pk_add_f32 v[64:65], v[90:91], v[72:73]
	v_pk_add_f32 v[64:65], v[96:97], v[64:65]
	s_nop 0
	v_pk_fma_f32 v[106:107], v[106:107], v[82:83], v[64:65]

; DEVI unsigned pk_bf16(float lo, float hi) { unsigned r; asm("v_cvt_pk_bf16_f32 %0, %1, %2" : "=v"(r) : "v"(lo), "v"(hi)); return r; }
; DEVI int otid() { int t = threadIdx.x; asm volatile("" : "+v"(t)); return t; }
; template <int DK, bool BIAS> ...
;     ...
;   for (int qi = 0; qi < 2; ++qi) {
;     const int qg = q0 + 32 * w + 16 * qi + fr;
;     float l = lrun[qi]; l += __shfl_xor(l, 16); l += __shfl_xor(l, 32);
;     const float inv = 1.0f / l;
;     if (qg < qend) {
; #pragma unroll
;       for (int et = 0; et < 4; ++et) { uint2 o; o.x = pk_bf16(O[et][qi][0] * inv, O[et][qi][1] * inv); o.y = pk_bf16(O[et][qi][2] * inv, O[et][qi][3] * inv);
;         *(uint2*)(Op + (size_t)(rowb + qg) * 1024 + 16 * et + 4 * fq) = o; }
;     }
;   }
; __device__ __forceinline__ void attn_phase(const Params& p, unsigned char* lds) {
;     ...
;     if (otid() == 0) s_item = (int)atomicAdd(ctr, 1u);
.LBB0_1801:
	s_mov_b32 s98, 1
	v_readlane_b32 s100, v254, 47
	v_readlane_b32 s101, v254, 48
	v_cmp_eq_u32_e32 vcc, 0, v128
	s_and_saveexec_b64 vcc, vcc
	v_mov_b32_e32 v251, 1
	s_nop 2
	global_atomic_add v251, v130, v251, s[100:101] sc0
	s_mov_b64 exec, vcc
	v_cmp_lt_i32_e32 vcc, v186, v184
	v_readlane_b32 s0, v254, 55
	s_add_u32 s0, s0, s36
	v_cndmask_b32_e32 v0, v183, v186, vcc
	v_lshlrev_b32_e32 v0, 2, v0
	ds_bpermute_b32 v2, v0, v107
	v_cmp_lt_i32_e32 vcc, v185, v184
	v_readlane_b32 s1, v254, 56
	s_addc_u32 s1, s1, 0
	v_cndmask_b32_e32 v1, v183, v185, vcc
	v_lshlrev_b32_e32 v1, 2, v1
	s_waitcnt lgkmcnt(0)
	v_add_f32_e32 v2, v107, v2
	ds_bpermute_b32 v3, v1, v2
	v_lshlrev_b32_e32 v4, 1, v103
	v_mov_b32_e32 v5, v130
	v_lshl_add_u64 v[4:5], s[0:1], 0, v[4:5]
	s_and_saveexec_b64 s[0:1], s[4:5]
	s_cbranch_execz .LBB0_1803
	s_waitcnt lgkmcnt(0)
	v_add_f32_e32 v2, v2, v3
	v_div_scale_f32 v3, s[4:5], v2, v2, 1.0
	v_rcp_f32_e32 v6, v3
	v_div_scale_f32 v7, vcc, 1.0, v2, 1.0
	v_fma_f32 v8, -v3, v6, 1.0
	v_fmac_f32_e32 v6, v8, v6
	v_mul_f32_e32 v8, v7, v6
	v_fma_f32 v9, -v3, v8, v7
	v_fmac_f32_e32 v8, v9, v6
	v_fma_f32 v3, -v3, v8, v7
	v_div_fmas_f32 v3, v3, v6, v8
	v_div_fixup_f32 v8, v3, v2, 1.0
	v_mul_f32_e32 v6, v48, v8
	v_mul_f32_e32 v7, v49, v8
	v_lshlrev_b64 v[2:3], 11, v[100:101]
	v_cvt_pk_bf16_f32 v6, v6, v7
	v_mul_f32_e32 v7, v50, v8
	v_lshl_add_u64 v[2:3], v[4:5], 0, v[2:3]
	v_mul_f32_e32 v9, v51, v8
	v_cvt_pk_bf16_f32 v7, v7, v9
	global_store_dwordx2 v[2:3], v[6:7], off
	v_mul_f32_e32 v6, v52, v8
	v_mul_f32_e32 v7, v53, v8
	v_cvt_pk_bf16_f32 v6, v6, v7
	v_mul_f32_e32 v7, v54, v8
	v_mul_f32_e32 v9, v55, v8
	v_cvt_pk_bf16_f32 v7, v7, v9
	global_store_dwordx2 v[2:3], v[6:7], off offset:32
	v_mul_f32_e32 v6, v56, v8
	v_mul_f32_e32 v7, v57, v8
	v_cvt_pk_bf16_f32 v6, v6, v7
	v_mul_f32_e32 v7, v58, v8
	v_mul_f32_e32 v9, v59, v8
	v_cvt_pk_bf16_f32 v7, v7, v9
	global_store_dwordx2 v[2:3], v[6:7], off offset:64
	v_mul_f32_e32 v6, v60, v8
	v_mul_f32_e32 v7, v61, v8
	v_cvt_pk_bf16_f32 v6, v6, v7
	v_mul_f32_e32 v7, v62, v8
	v_mul_f32_e32 v8, v63, v8
	v_cvt_pk_bf16_f32 v7, v7, v8
	global_store_dwordx2 v[2:3], v[6:7], off offset:96

; DEVI unsigned pk_bf16(float lo, float hi) { unsigned r; asm("v_cvt_pk_bf16_f32 %0, %1, %2" : "=v"(r) : "v"(lo), "v"(hi)); return r; }
; DEVI bf16x8 mk8(uint2 a, uint2 b) { union { uint4 u; bf16x8 v; } c; c.u = make_uint4(a.x, a.y, b.x, b.y); return c.v; }
; template <int DK, bool BIAS> ...
;     ...
;         } else {
; #pragma unroll
;           for (int kt = 0; kt < 4; ++kt)
; #pragma unroll
;             for (int r = 0; r < 4; ++r) mx = fmaxf(mx, S[kt][qi][r]);
;           mx *= sc2;
;         }
;         mx = fmaxf(mx, __shfl_xor(mx, 16)); mx = fmaxf(mx, __shfl_xor(mx, 32));
;         const float mold = mrun[qi], mnew = fmaxf(mold, mx);
;         mrun[qi] = mnew;
;         float ps = 0.f;
; #pragma unroll
;         for (int kt = 0; kt < 4; ++kt)
; #pragma unroll
;           for (int r = 0; r < 4; ++r) { const float pv = BIAS ? __builtin_amdgcn_exp2f(S[kt][qi][r] - mnew) : __builtin_amdgcn_exp2f(fmaf(S[kt][qi][r], sc2, -mnew)); S[kt][qi][r] = pv; ps += pv; }
;         {
;           const float alpha = __builtin_amdgcn_exp2f(mold - mnew);
;           lrun[qi] *= alpha;
; #pragma unroll
;           for (int et = 0; et < 4; ++et) O[et][qi] *= alpha;
;         }
;         lrun[qi] += ps;
; #pragma unroll
;         for (int k2 = 0; k2 < 2; ++k2) { uint2 lo, hi; lo.x = pk_bf16(S[2 * k2][qi][0], S[2 * k2][qi][1]); lo.y = pk_bf16(S[2 * k2][qi][2], S[2 * k2][qi][3]);
;           hi.x = pk_bf16(S[2 * k2 + 1][qi][0], S[2 * k2 + 1][qi][1]); hi.y = pk_bf16(S[2 * k2 + 1][qi][2], S[2 * k2 + 1][qi][3]); pf[qi][k2] = mk8(lo, hi); }
;       }
.LBB0_1866:
	s_or_b64 exec, exec, s[18:19]
	s_mov_b32 s100, s34
	s_mov_b32 s101, s34
	v_lshlrev_b32_e32 v250, 2, v186
	v_max3_f32 v242, v96, s31, v97
	v_max3_f32 v243, v84, s31, v85
	v_max3_f32 v242, v242, v98, v99
	v_max3_f32 v243, v243, v86, v87
	v_max3_f32 v242, v242, v100, v101
	v_max3_f32 v243, v243, v88, v89
	v_max3_f32 v242, v242, v102, v103
	v_max3_f32 v243, v243, v90, v91
	v_max3_f32 v242, v242, v104, v105
	v_max3_f32 v243, v243, v80, v81
	v_max3_f32 v242, v242, v106, v107
	v_max3_f32 v243, v243, v82, v83
	v_max3_f32 v242, v242, v108, v109
	v_max3_f32 v243, v243, v92, v93
	v_max3_f32 v242, v242, v110, v111
	v_max3_f32 v243, v243, v94, v95
	v_mul_f32_e32 v242, 0x3e16c740, v242
	v_mul_f32_e32 v243, 0x3e16c740, v243
	ds_bpermute_b32 v244, v250, v242
	ds_bpermute_b32 v245, v250, v243
	s_waitcnt lgkmcnt(0)
	v_max_f32_e32 v242, v242, v244
	v_max_f32_e32 v243, v243, v245
	v_lshlrev_b32_e32 v250, 2, v185
	ds_bpermute_b32 v244, v250, v242
	ds_bpermute_b32 v245, v250, v243
	s_waitcnt lgkmcnt(0)
	v_max3_f32 v131, v154, v242, v244
	v_max3_f32 v209, v208, v243, v245
	v_sub_f32_e32 v242, v154, v131
	v_sub_f32_e32 v243, v208, v209
	v_sub_f32_e32 v246, 0, v131
	v_sub_f32_e32 v248, 0, v209
	v_pk_fma_f32 v[210:211], v[96:97], s[100:101], v[246:247] op_sel_hi:[1,1,0]
	v_pk_fma_f32 v[226:227], v[80:81], s[100:101], v[248:249] op_sel_hi:[1,1,0]
	v_pk_fma_f32 v[212:213], v[98:99], s[100:101], v[246:247] op_sel_hi:[1,1,0]
	v_pk_fma_f32 v[228:229], v[82:83], s[100:101], v[248:249] op_sel_hi:[1,1,0]
	v_pk_fma_f32 v[214:215], v[100:101], s[100:101], v[246:247] op_sel_hi:[1,1,0]
	v_pk_fma_f32 v[230:231], v[84:85], s[100:101], v[248:249] op_sel_hi:[1,1,0]
	v_pk_fma_f32 v[216:217], v[102:103], s[100:101], v[246:247] op_sel_hi:[1,1,0]
	v_pk_fma_f32 v[232:233], v[86:87], s[100:101], v[248:249] op_sel_hi:[1,1,0]
	v_pk_fma_f32 v[218:219], v[104:105], s[100:101], v[246:247] op_sel_hi:[1,1,0]
	v_pk_fma_f32 v[234:235], v[88:89], s[100:101], v[248:249] op_sel_hi:[1,1,0]
	v_pk_fma_f32 v[220:221], v[106:107], s[100:101], v[246:247] op_sel_hi:[1,1,0]
	v_pk_fma_f32 v[236:237], v[90:91], s[100:101], v[248:249] op_sel_hi:[1,1,0]
	v_pk_fma_f32 v[222:223], v[108:109], s[100:101], v[246:247] op_sel_hi:[1,1,0]
	v_pk_fma_f32 v[238:239], v[92:93], s[100:101], v[248:249] op_sel_hi:[1,1,0]
	v_pk_fma_f32 v[224:225], v[110:111], s[100:101], v[246:247] op_sel_hi:[1,1,0]
	v_pk_fma_f32 v[240:241], v[94:95], s[100:101], v[248:249] op_sel_hi:[1,1,0]
	v_exp_f32_e32 v178, v242
	v_exp_f32_e32 v90, v243
	v_exp_f32_e32 v163, v210
	v_exp_f32_e32 v170, v226
	v_exp_f32_e32 v165, v211
	v_exp_f32_e32 v104, v227
	v_exp_f32_e32 v167, v212
	v_exp_f32_e32 v172, v228
	v_exp_f32_e32 v169, v213
	v_exp_f32_e32 v106, v229
	v_exp_f32_e32 v155, v214
	v_exp_f32_e32 v162, v230
	v_exp_f32_e32 v157, v215
	v_exp_f32_e32 v164, v231
	v_exp_f32_e32 v159, v216
	v_exp_f32_e32 v166, v232
	v_exp_f32_e32 v161, v217
	v_exp_f32_e32 v168, v233
	v_exp_f32_e32 v171, v218
	v_exp_f32_e32 v154, v234
	v_exp_f32_e32 v105, v219
	v_exp_f32_e32 v156, v235
	v_exp_f32_e32 v173, v220
	v_exp_f32_e32 v158, v236
	v_exp_f32_e32 v107, v221
	v_exp_f32_e32 v160, v237
	v_exp_f32_e32 v175, v222
	v_exp_f32_e32 v174, v238
	v_exp_f32_e32 v109, v223
	v_exp_f32_e32 v108, v239
	v_exp_f32_e32 v177, v224
	v_exp_f32_e32 v176, v240
	v_exp_f32_e32 v111, v225
	v_exp_f32_e32 v110, v241
	v_pk_add_f32 v[80:81], v[154:155], 0 op_sel_hi:[1,0]
	v_pk_add_f32 v[80:81], v[156:157], v[80:81]
	v_pk_add_f32 v[80:81], v[158:159], v[80:81]
	v_pk_add_f32 v[80:81], v[160:161], v[80:81]
	v_pk_add_f32 v[80:81], v[162:163], v[80:81]
	v_pk_mul_f32 v[102:103], v[66:67], v[178:179] op_sel_hi:[1,0]
	v_pk_add_f32 v[80:81], v[164:165], v[80:81]
	v_pk_mul_f32 v[100:101], v[64:65], v[178:179] op_sel_hi:[1,0]
	v_pk_add_f32 v[80:81], v[166:167], v[80:81]
	v_pk_mul_f32 v[64:65], v[76:77], v[178:179] op_sel_hi:[1,0]
	v_pk_add_f32 v[80:81], v[168:169], v[80:81]
	v_cvt_pk_bf16_f32 v76, v171, v105
	v_pk_mul_f32 v[98:99], v[70:71], v[178:179] op_sel_hi:[1,0]
	v_pk_add_f32 v[80:81], v[170:171], v[80:81]
	v_pk_mul_f32 v[96:97], v[68:69], v[178:179] op_sel_hi:[1,0]
	v_pk_add_f32 v[88:89], v[104:105], v[80:81]
	v_add_u32_e32 v105, 0x7000, v203
	v_cvt_pk_bf16_f32 v68, v155, v157
	v_cvt_pk_bf16_f32 v69, v159, v161
	v_pk_mul_f32 v[84:85], v[52:53], v[90:91] op_sel_hi:[1,0]
	v_pk_add_f32 v[52:53], v[172:173], v[88:89]
	v_pk_mul_f32 v[82:83], v[50:51], v[90:91] op_sel_hi:[1,0]
	v_pk_add_f32 v[52:53], v[106:107], v[52:53]
	v_pk_mul_f32 v[80:81], v[48:49], v[90:91] op_sel_hi:[1,0]
	v_pk_add_f32 v[52:53], v[174:175], v[52:53]
	v_pk_mul_f32 v[86:87], v[54:55], v[90:91] op_sel_hi:[1,0]
	v_pk_add_f32 v[52:53], v[108:109], v[52:53]
	v_pk_mul_f32 v[58:59], v[58:59], v[90:91] op_sel_hi:[1,0]
	v_pk_add_f32 v[52:53], v[176:177], v[52:53]
	v_pk_mul_f32 v[56:57], v[56:57], v[90:91] op_sel_hi:[1,0]
	v_pk_mul_f32 v[50:51], v[62:63], v[90:91] op_sel_hi:[1,0]
	v_pk_mul_f32 v[48:49], v[60:61], v[90:91] op_sel_hi:[1,0]
	v_mov_b32_e32 v91, v178
	v_pk_add_f32 v[52:53], v[110:111], v[52:53]
	v_cvt_pk_bf16_f32 v60, v170, v104
	v_add_u32_e32 v104, 0x6800, v203
	v_pk_fma_f32 v[120:121], v[120:121], v[90:91], v[52:53]
	ds_read2_b64 v[88:91], v104 offset1:4
	v_cvt_pk_bf16_f32 v70, v163, v165
	v_cvt_pk_bf16_f32 v71, v167, v169
	v_cvt_pk_bf16_f32 v52, v154, v156
	v_cvt_pk_bf16_f32 v53, v158, v160
	v_cvt_pk_bf16_f32 v54, v162, v164
	v_cvt_pk_bf16_f32 v55, v166, v168
	v_cvt_pk_bf16_f32 v61, v172, v106
	s_waitcnt lgkmcnt(0)
; DEVI bf16x8 mk8(uint2 a, uint2 b) { union { uint4 u; bf16x8 v; } c; c.u = make_uint4(a.x, a.y, b.x, b.y); return c.v; }
; #define MFMA(a, b, c) __builtin_amdgcn_mfma_f32_16x16x32_bf16((a), (b), (c), 0, 0, 0)
; template <int DK, bool BIAS> ...
;     ...
; #pragma unroll
;       for (int k2 = 0; k2 < 2; ++k2)
; #pragma unroll
;         for (int et = 0; et < 4; ++et) {
;           const uint2 v0 = *(const uint2*)(Vtm + (buf * 64 + 16 * et + fr) * 72 + 32 * k2 + 4 * fq), v1 = *(const uint2*)(Vtm + (buf * 64 + 16 * et + fr) * 72 + 32 * k2 + 16 + 4 * fq);
;           const bf16x8 va = mk8(v0, v1);
; #pragma unroll
;           for (int qi = 0; qi < 2; ++qi) O[et][qi] = MFMA(va, pf[qi][k2], O[et][qi]);
;         }
	v_mfma_f32_16x16x32_bf16 v[92:95], v[88:91], v[68:71], v[100:103]
	v_add_u32_e32 v106, 0x7800, v203
	v_pk_mul_f32 v[74:75], v[74:75], v[178:179] op_sel_hi:[1,0]
	v_pk_mul_f32 v[72:73], v[72:73], v[178:179] op_sel_hi:[1,0]
	v_mfma_f32_16x16x32_bf16 v[80:83], v[88:91], v[52:55], v[80:83]
	ds_read2_b64 v[88:91], v105 offset0:32 offset1:36
	v_cvt_pk_bf16_f32 v77, v173, v107
	v_add_u32_e32 v107, 0x8000, v203
	s_waitcnt lgkmcnt(0)
	v_mfma_f32_16x16x32_bf16 v[96:99], v[88:91], v[68:71], v[96:99]
	v_pk_mul_f32 v[66:67], v[78:79], v[178:179] op_sel_hi:[1,0]
	v_cvt_pk_bf16_f32 v78, v175, v109
	v_cvt_pk_bf16_f32 v79, v177, v111
	v_mfma_f32_16x16x32_bf16 v[84:87], v[88:91], v[52:55], v[84:87]
	ds_read2_b64 v[88:91], v106 offset0:64 offset1:68
	v_cvt_pk_bf16_f32 v62, v174, v108
	v_cvt_pk_bf16_f32 v63, v176, v110
	s_waitcnt lgkmcnt(0)
	v_mfma_f32_16x16x32_bf16 v[72:75], v[88:91], v[68:71], v[72:75]
	v_mov_b32_e32 v208, v209
	v_mov_b32_e32 v154, v131
	v_mfma_f32_16x16x32_bf16 v[56:59], v[88:91], v[52:55], v[56:59]
	ds_read2_b64 v[88:91], v107 offset0:96 offset1:100
	s_waitcnt lgkmcnt(0)
	v_mfma_f32_16x16x32_bf16 v[100:103], v[88:91], v[68:71], v[64:67]
	v_mfma_f32_16x16x32_bf16 v[88:91], v[88:91], v[52:55], v[48:51]
	ds_read2_b64 v[52:55], v105 offset0:40 offset1:44
	s_nop 1
	ds_read2_b64 v[48:51], v104 offset0:8 offset1:12
	s_waitcnt lgkmcnt(0)
	v_mfma_f32_16x16x32_bf16 v[64:67], v[48:51], v[76:79], v[92:95]
	v_mfma_f32_16x16x32_bf16 v[48:51], v[48:51], v[60:63], v[80:83]
	s_nop 2
	ds_read2_b64 v[80:83], v106 offset0:72 offset1:76
	s_waitcnt lgkmcnt(0)
	v_mfma_f32_16x16x32_bf16 v[72:75], v[80:83], v[76:79], v[72:75]
	v_mfma_f32_16x16x32_bf16 v[56:59], v[80:83], v[60:63], v[56:59]
	ds_read2_b64 v[80:83], v107 offset0:104 offset1:108
	v_mfma_f32_16x16x32_bf16 v[68:71], v[52:55], v[76:79], v[96:99]
	v_mfma_f32_16x16x32_bf16 v[52:55], v[52:55], v[60:63], v[84:87]
	s_waitcnt lgkmcnt(0)
	v_mfma_f32_16x16x32_bf16 v[76:79], v[80:83], v[76:79], v[100:103]
	v_mfma_f32_16x16x32_bf16 v[60:63], v[80:83], v[60:63], v[88:91]

; DEVI unsigned pk_bf16(float lo, float hi) { unsigned r; asm("v_cvt_pk_bf16_f32 %0, %1, %2" : "=v"(r) : "v"(lo), "v"(hi)); return r; }
; DEVI bf16x8 mk8(uint2 a, uint2 b) { union { uint4 u; bf16x8 v; } c; c.u = make_uint4(a.x, a.y, b.x, b.y); return c.v; }
; template <int DK, bool BIAS> ...
;     ...
;         } else {
; #pragma unroll
;           for (int kt = 0; kt < 4; ++kt)
; #pragma unroll
;             for (int r = 0; r < 4; ++r) mx = fmaxf(mx, S[kt][qi][r]);
;           mx *= sc2;
;         }
;         mx = fmaxf(mx, __shfl_xor(mx, 16)); mx = fmaxf(mx, __shfl_xor(mx, 32));
;         const float mold = mrun[qi], mnew = fmaxf(mold, mx);
;         mrun[qi] = mnew;
;         float ps = 0.f;
; #pragma unroll
;         for (int kt = 0; kt < 4; ++kt)
; #pragma unroll
;           for (int r = 0; r < 4; ++r) { const float pv = BIAS ? __builtin_amdgcn_exp2f(S[kt][qi][r] - mnew) : __builtin_amdgcn_exp2f(fmaf(S[kt][qi][r], sc2, -mnew)); S[kt][qi][r] = pv; ps += pv; }
;         {
;           const float alpha = __builtin_amdgcn_exp2f(mold - mnew);
;           lrun[qi] *= alpha;
; #pragma unroll
;           for (int et = 0; et < 4; ++et) O[et][qi] *= alpha;
;         }
;         lrun[qi] += ps;
; #pragma unroll
;         for (int k2 = 0; k2 < 2; ++k2) { uint2 lo, hi; lo.x = pk_bf16(S[2 * k2][qi][0], S[2 * k2][qi][1]); lo.y = pk_bf16(S[2 * k2][qi][2], S[2 * k2][qi][3]);
;           hi.x = pk_bf16(S[2 * k2 + 1][qi][0], S[2 * k2 + 1][qi][1]); hi.y = pk_bf16(S[2 * k2 + 1][qi][2], S[2 * k2 + 1][qi][3]); pf[qi][k2] = mk8(lo, hi); }
;       }
.LBB0_1888:
	s_or_b64 exec, exec, s[18:19]
	s_mov_b32 s100, s34
	s_mov_b32 s101, s34
	v_lshlrev_b32_e32 v250, 2, v186
	v_max3_f32 v242, v96, s31, v97
	v_max3_f32 v243, v84, s31, v85
	v_max3_f32 v242, v242, v98, v99
	v_max3_f32 v243, v243, v86, v87
	v_max3_f32 v242, v242, v100, v101
	v_max3_f32 v243, v243, v88, v89
	v_max3_f32 v242, v242, v102, v103
	v_max3_f32 v243, v243, v90, v91
	v_max3_f32 v242, v242, v104, v105
	v_max3_f32 v243, v243, v80, v81
	v_max3_f32 v242, v242, v106, v107
	v_max3_f32 v243, v243, v82, v83
	v_max3_f32 v242, v242, v108, v109
	v_max3_f32 v243, v243, v92, v93
	v_max3_f32 v242, v242, v110, v111
	v_max3_f32 v243, v243, v94, v95
	v_mul_f32_e32 v242, 0x3e16c740, v242
	v_mul_f32_e32 v243, 0x3e16c740, v243
	ds_bpermute_b32 v244, v250, v242
	ds_bpermute_b32 v245, v250, v243
	s_waitcnt lgkmcnt(0)
	v_max_f32_e32 v242, v242, v244
	v_max_f32_e32 v243, v243, v245
	v_lshlrev_b32_e32 v250, 2, v185
	ds_bpermute_b32 v244, v250, v242
	ds_bpermute_b32 v245, v250, v243
	s_waitcnt lgkmcnt(0)
	v_max3_f32 v131, v154, v242, v244
	v_max3_f32 v209, v208, v243, v245
	v_sub_f32_e32 v242, v154, v131
	v_sub_f32_e32 v243, v208, v209
	v_sub_f32_e32 v246, 0, v131
	v_sub_f32_e32 v248, 0, v209
	v_pk_fma_f32 v[210:211], v[96:97], s[100:101], v[246:247] op_sel_hi:[1,1,0]
	v_pk_fma_f32 v[226:227], v[80:81], s[100:101], v[248:249] op_sel_hi:[1,1,0]
	v_pk_fma_f32 v[212:213], v[98:99], s[100:101], v[246:247] op_sel_hi:[1,1,0]
	v_pk_fma_f32 v[228:229], v[82:83], s[100:101], v[248:249] op_sel_hi:[1,1,0]
	v_pk_fma_f32 v[214:215], v[100:101], s[100:101], v[246:247] op_sel_hi:[1,1,0]
	v_pk_fma_f32 v[230:231], v[84:85], s[100:101], v[248:249] op_sel_hi:[1,1,0]
	v_pk_fma_f32 v[216:217], v[102:103], s[100:101], v[246:247] op_sel_hi:[1,1,0]
	v_pk_fma_f32 v[232:233], v[86:87], s[100:101], v[248:249] op_sel_hi:[1,1,0]
	v_pk_fma_f32 v[218:219], v[104:105], s[100:101], v[246:247] op_sel_hi:[1,1,0]
	v_pk_fma_f32 v[234:235], v[88:89], s[100:101], v[248:249] op_sel_hi:[1,1,0]
	v_pk_fma_f32 v[220:221], v[106:107], s[100:101], v[246:247] op_sel_hi:[1,1,0]
	v_pk_fma_f32 v[236:237], v[90:91], s[100:101], v[248:249] op_sel_hi:[1,1,0]
	v_pk_fma_f32 v[222:223], v[108:109], s[100:101], v[246:247] op_sel_hi:[1,1,0]
	v_pk_fma_f32 v[238:239], v[92:93], s[100:101], v[248:249] op_sel_hi:[1,1,0]
	v_pk_fma_f32 v[224:225], v[110:111], s[100:101], v[246:247] op_sel_hi:[1,1,0]
	v_pk_fma_f32 v[240:241], v[94:95], s[100:101], v[248:249] op_sel_hi:[1,1,0]
	v_exp_f32_e32 v178, v242
	v_exp_f32_e32 v90, v243
	v_exp_f32_e32 v163, v210
	v_exp_f32_e32 v162, v226
	v_exp_f32_e32 v165, v211
	v_exp_f32_e32 v164, v227
	v_exp_f32_e32 v167, v212
	v_exp_f32_e32 v166, v228
	v_exp_f32_e32 v169, v213
	v_exp_f32_e32 v168, v229
	v_exp_f32_e32 v155, v214
	v_exp_f32_e32 v170, v230
	v_exp_f32_e32 v157, v215
	v_exp_f32_e32 v104, v231
	v_exp_f32_e32 v159, v216
	v_exp_f32_e32 v172, v232
	v_exp_f32_e32 v161, v217
	v_exp_f32_e32 v106, v233
	v_exp_f32_e32 v171, v218
	v_exp_f32_e32 v154, v234
	v_exp_f32_e32 v105, v219
	v_exp_f32_e32 v156, v235
	v_exp_f32_e32 v173, v220
	v_exp_f32_e32 v158, v236
	v_exp_f32_e32 v107, v221
	v_exp_f32_e32 v160, v237
	v_exp_f32_e32 v175, v222
	v_exp_f32_e32 v174, v238
	v_exp_f32_e32 v109, v223
	v_exp_f32_e32 v108, v239
	v_exp_f32_e32 v177, v224
	v_exp_f32_e32 v176, v240
	v_exp_f32_e32 v111, v225
	v_exp_f32_e32 v110, v241
	v_pk_add_f32 v[80:81], v[154:155], 0 op_sel_hi:[1,0]
	v_pk_add_f32 v[80:81], v[156:157], v[80:81]
	v_pk_mul_f32 v[102:103], v[66:67], v[178:179] op_sel_hi:[1,0]
	v_pk_add_f32 v[80:81], v[158:159], v[80:81]
	v_pk_mul_f32 v[100:101], v[64:65], v[178:179] op_sel_hi:[1,0]
	v_pk_add_f32 v[80:81], v[160:161], v[80:81]
	v_pk_mul_f32 v[64:65], v[76:77], v[178:179] op_sel_hi:[1,0]
	v_pk_add_f32 v[80:81], v[162:163], v[80:81]
	v_cvt_pk_bf16_f32 v76, v171, v105
	v_pk_mul_f32 v[98:99], v[70:71], v[178:179] op_sel_hi:[1,0]
	v_pk_add_f32 v[80:81], v[164:165], v[80:81]
	v_pk_mul_f32 v[96:97], v[68:69], v[178:179] op_sel_hi:[1,0]
	v_pk_add_f32 v[88:89], v[166:167], v[80:81]
	v_cvt_pk_bf16_f32 v68, v155, v157
	v_cvt_pk_bf16_f32 v69, v159, v161
	v_cvt_pk_bf16_f32 v70, v163, v165
	v_cvt_pk_bf16_f32 v71, v167, v169
	v_pk_mul_f32 v[74:75], v[74:75], v[178:179] op_sel_hi:[1,0]
	v_pk_mul_f32 v[84:85], v[52:53], v[90:91] op_sel_hi:[1,0]
	v_pk_add_f32 v[52:53], v[168:169], v[88:89]
	v_pk_mul_f32 v[82:83], v[50:51], v[90:91] op_sel_hi:[1,0]
	v_pk_add_f32 v[52:53], v[170:171], v[52:53]
	v_pk_mul_f32 v[80:81], v[48:49], v[90:91] op_sel_hi:[1,0]
	v_pk_add_f32 v[52:53], v[104:105], v[52:53]
	v_pk_mul_f32 v[86:87], v[54:55], v[90:91] op_sel_hi:[1,0]
	v_pk_add_f32 v[52:53], v[172:173], v[52:53]
	v_pk_mul_f32 v[58:59], v[58:59], v[90:91] op_sel_hi:[1,0]
	v_pk_add_f32 v[52:53], v[106:107], v[52:53]
	v_pk_mul_f32 v[56:57], v[56:57], v[90:91] op_sel_hi:[1,0]
	v_pk_add_f32 v[52:53], v[174:175], v[52:53]
	v_pk_mul_f32 v[50:51], v[62:63], v[90:91] op_sel_hi:[1,0]
	v_pk_add_f32 v[52:53], v[108:109], v[52:53]
	v_pk_mul_f32 v[48:49], v[60:61], v[90:91] op_sel_hi:[1,0]
	v_pk_add_f32 v[52:53], v[176:177], v[52:53]
	v_mov_b32_e32 v91, v178
	v_pk_add_f32 v[52:53], v[110:111], v[52:53]
	v_cvt_pk_bf16_f32 v60, v170, v104
	v_add_u32_e32 v104, 0x6800, v206
	v_pk_fma_f32 v[120:121], v[120:121], v[90:91], v[52:53]
	ds_read2_b64 v[88:91], v104 offset1:4
	v_add_u32_e32 v105, 0x9000, v203
	v_cvt_pk_bf16_f32 v52, v154, v156
	v_cvt_pk_bf16_f32 v53, v158, v160
	v_cvt_pk_bf16_f32 v54, v162, v164
	v_cvt_pk_bf16_f32 v55, v166, v168
	s_waitcnt lgkmcnt(0)
; DEVI bf16x8 mk8(uint2 a, uint2 b) { union { uint4 u; bf16x8 v; } c; c.u = make_uint4(a.x, a.y, b.x, b.y); return c.v; }
; #define MFMA(a, b, c) __builtin_amdgcn_mfma_f32_16x16x32_bf16((a), (b), (c), 0, 0, 0)
; template <int DK, bool BIAS> ...
;     ...
; #pragma unroll
;       for (int k2 = 0; k2 < 2; ++k2)
; #pragma unroll
;         for (int et = 0; et < 4; ++et) {
;           const uint2 v0 = *(const uint2*)(Vtm + (buf * 64 + 16 * et + fr) * 72 + 32 * k2 + 4 * fq), v1 = *(const uint2*)(Vtm + (buf * 64 + 16 * et + fr) * 72 + 32 * k2 + 16 + 4 * fq);
;           const bf16x8 va = mk8(v0, v1);
; #pragma unroll
;           for (int qi = 0; qi < 2; ++qi) O[et][qi] = MFMA(va, pf[qi][k2], O[et][qi]);
;         }
	v_mfma_f32_16x16x32_bf16 v[92:95], v[88:91], v[68:71], v[100:103]
	v_cvt_pk_bf16_f32 v61, v172, v106
	v_add_u32_e32 v106, 0x9800, v203
	v_pk_mul_f32 v[72:73], v[72:73], v[178:179] op_sel_hi:[1,0]
	v_mfma_f32_16x16x32_bf16 v[80:83], v[88:91], v[52:55], v[80:83]
	ds_read2_b64 v[88:91], v105 offset0:160 offset1:164
	v_cvt_pk_bf16_f32 v77, v173, v107
	v_add_u32_e32 v107, 0xa000, v203
	s_waitcnt lgkmcnt(0)
	v_mfma_f32_16x16x32_bf16 v[96:99], v[88:91], v[68:71], v[96:99]
	v_pk_mul_f32 v[66:67], v[78:79], v[178:179] op_sel_hi:[1,0]
	v_cvt_pk_bf16_f32 v78, v175, v109
	v_cvt_pk_bf16_f32 v79, v177, v111
	v_mfma_f32_16x16x32_bf16 v[84:87], v[88:91], v[52:55], v[84:87]
	ds_read2_b64 v[88:91], v106 offset0:192 offset1:196
	v_cvt_pk_bf16_f32 v62, v174, v108
	v_cvt_pk_bf16_f32 v63, v176, v110
	s_waitcnt lgkmcnt(0)
	v_mfma_f32_16x16x32_bf16 v[72:75], v[88:91], v[68:71], v[72:75]
	v_mov_b32_e32 v208, v209
	v_mov_b32_e32 v154, v131
	v_mfma_f32_16x16x32_bf16 v[56:59], v[88:91], v[52:55], v[56:59]
	ds_read2_b64 v[88:91], v107 offset0:224 offset1:228
	s_waitcnt lgkmcnt(0)
	v_mfma_f32_16x16x32_bf16 v[100:103], v[88:91], v[68:71], v[64:67]
	v_mfma_f32_16x16x32_bf16 v[88:91], v[88:91], v[52:55], v[48:51]
	ds_read2_b64 v[52:55], v105 offset0:168 offset1:172
	s_nop 1
	ds_read2_b64 v[48:51], v104 offset0:8 offset1:12
	s_waitcnt lgkmcnt(0)
	v_mfma_f32_16x16x32_bf16 v[64:67], v[48:51], v[76:79], v[92:95]
	v_mfma_f32_16x16x32_bf16 v[48:51], v[48:51], v[60:63], v[80:83]
	s_nop 2
	ds_read2_b64 v[80:83], v106 offset0:200 offset1:204
	s_waitcnt lgkmcnt(0)
	v_mfma_f32_16x16x32_bf16 v[72:75], v[80:83], v[76:79], v[72:75]
	v_mfma_f32_16x16x32_bf16 v[56:59], v[80:83], v[60:63], v[56:59]
	ds_read2_b64 v[80:83], v107 offset0:232 offset1:236
	v_mfma_f32_16x16x32_bf16 v[68:71], v[52:55], v[76:79], v[96:99]
	v_mfma_f32_16x16x32_bf16 v[52:55], v[52:55], v[60:63], v[84:87]
	s_waitcnt lgkmcnt(0)
	v_mfma_f32_16x16x32_bf16 v[76:79], v[80:83], v[76:79], v[100:103]
	v_mfma_f32_16x16x32_bf16 v[60:63], v[80:83], v[60:63], v[88:91]

; DEVI unsigned pk_bf16(float lo, float hi) { unsigned r; asm("v_cvt_pk_bf16_f32 %0, %1, %2" : "=v"(r) : "v"(lo), "v"(hi)); return r; }
; DEVI int otid() { int t = threadIdx.x; asm volatile("" : "+v"(t)); return t; }
; template <int DK, bool BIAS> ...
;     ...
;   for (int qi = 0; qi < 2; ++qi) {
;     const int qg = q0 + 32 * w + 16 * qi + fr;
;     float l = lrun[qi]; l += __shfl_xor(l, 16); l += __shfl_xor(l, 32);
;     const float inv = 1.0f / l;
;     if (qg < qend) {
; #pragma unroll
;       for (int et = 0; et < 4; ++et) { uint2 o; o.x = pk_bf16(O[et][qi][0] * inv, O[et][qi][1] * inv); o.y = pk_bf16(O[et][qi][2] * inv, O[et][qi][3] * inv);
;         *(uint2*)(Op + (size_t)(rowb + qg) * 1024 + 16 * et + 4 * fq) = o; }
;     }
;   }
; __device__ __forceinline__ void attn_phase(const Params& p, unsigned char* lds) {
;     ...
;     if (otid() == 0) s_item = (int)atomicAdd(ctr, 1u);
.LBB0_1891:
	s_mov_b32 s98, 1
	v_readlane_b32 s100, v254, 47
	v_readlane_b32 s101, v254, 48
	v_cmp_eq_u32_e32 vcc, 0, v128
	s_and_saveexec_b64 vcc, vcc
	v_mov_b32_e32 v251, 1
	s_nop 2
	global_atomic_add v251, v130, v251, s[100:101] sc0
	s_mov_b64 exec, vcc
	v_cmp_lt_i32_e32 vcc, v186, v184
	s_lshl_b32 s0, s20, 7
	v_readlane_b32 s6, v254, 18
	v_cndmask_b32_e32 v0, v183, v186, vcc
	v_lshlrev_b32_e32 v0, 2, v0
	ds_bpermute_b32 v2, v0, v121
	v_cmp_lt_i32_e32 vcc, v185, v184
	v_readlane_b32 s7, v254, 19
	s_add_u32 s0, s6, s0
	v_cndmask_b32_e32 v1, v183, v185, vcc
	v_lshlrev_b32_e32 v1, 2, v1
	s_waitcnt lgkmcnt(0)
	v_add_f32_e32 v2, v121, v2
	ds_bpermute_b32 v3, v1, v2
	s_addc_u32 s1, s7, 0
	v_lshlrev_b32_e32 v4, 1, v200
	v_mov_b32_e32 v5, v130
	v_lshl_add_u64 v[4:5], s[0:1], 0, v[4:5]
	s_and_saveexec_b64 s[0:1], s[2:3]
	s_cbranch_execz .LBB0_1893
	s_waitcnt lgkmcnt(0)
	v_add_f32_e32 v2, v2, v3
	v_div_scale_f32 v3, s[2:3], v2, v2, 1.0
	v_rcp_f32_e32 v6, v3
	v_div_scale_f32 v7, vcc, 1.0, v2, 1.0
	v_fma_f32 v8, -v3, v6, 1.0
	v_fmac_f32_e32 v6, v8, v6
	v_mul_f32_e32 v8, v7, v6
	v_fma_f32 v9, -v3, v8, v7
	v_fmac_f32_e32 v8, v9, v6
	v_fma_f32 v3, -v3, v8, v7
	v_div_fmas_f32 v3, v3, v6, v8
	v_div_fixup_f32 v8, v3, v2, 1.0
	v_mul_f32_e32 v6, v64, v8
	v_mul_f32_e32 v7, v65, v8
	v_lshlrev_b64 v[2:3], 11, v[112:113]
	v_cvt_pk_bf16_f32 v6, v6, v7
	v_mul_f32_e32 v7, v66, v8
	v_lshl_add_u64 v[2:3], v[4:5], 0, v[2:3]
	v_mul_f32_e32 v9, v67, v8
	v_cvt_pk_bf16_f32 v7, v7, v9
	global_store_dwordx2 v[2:3], v[6:7], off
	v_mul_f32_e32 v6, v68, v8
	v_mul_f32_e32 v7, v69, v8
	v_cvt_pk_bf16_f32 v6, v6, v7
	v_mul_f32_e32 v7, v70, v8
	v_mul_f32_e32 v9, v71, v8
	v_cvt_pk_bf16_f32 v7, v7, v9
	global_store_dwordx2 v[2:3], v[6:7], off offset:32
	v_mul_f32_e32 v6, v72, v8
	v_mul_f32_e32 v7, v73, v8
	v_cvt_pk_bf16_f32 v6, v6, v7
	v_mul_f32_e32 v7, v74, v8
	v_mul_f32_e32 v9, v75, v8
	v_cvt_pk_bf16_f32 v7, v7, v9
	global_store_dwordx2 v[2:3], v[6:7], off offset:64
	v_mul_f32_e32 v6, v76, v8
	v_mul_f32_e32 v7, v77, v8
	v_cvt_pk_bf16_f32 v6, v6, v7
	v_mul_f32_e32 v7, v78, v8
	v_mul_f32_e32 v8, v79, v8
	v_cvt_pk_bf16_f32 v7, v7, v8
	global_store_dwordx2 v[2:3], v[6:7], off offset:96
